# mix1a depthwise-conv FIR loop regenerated with 8-deep pipelined LDS reads (same FMA order), on v20
# speedup vs baseline: 1.0197x; 1.0025x over previous
.LBB0_538:
	v_add_u32_e32 v4, s0, v3
	ds_read_u16 v110, v4
	ds_read_u16 v111, v4 offset:512
	ds_read_u16 v112, v4 offset:1024
	ds_read_u16 v113, v4 offset:1536
	ds_read_u16 v114, v4 offset:2048
	ds_read_u16 v115, v4 offset:2560
	ds_read_u16 v116, v4 offset:3072
	ds_read_u16 v117, v4 offset:3584
	s_waitcnt lgkmcnt(7)
	v_lshlrev_b32_e32 v110, 16, v110
	v_fma_f32 v5, v30, v110, v27
	ds_read_u16 v110, v4 offset:4096
	s_waitcnt lgkmcnt(7)
	v_lshlrev_b32_e32 v111, 16, v111
	v_fmac_f32_e32 v5, v31, v111
	v_fma_f32 v6, v30, v111, v27
	ds_read_u16 v111, v4 offset:4608
	s_waitcnt lgkmcnt(7)
	v_lshlrev_b32_e32 v112, 16, v112
	v_fmac_f32_e32 v5, v32, v112
	v_fmac_f32_e32 v6, v31, v112
	v_fma_f32 v7, v30, v112, v27
	ds_read_u16 v112, v4 offset:5120
	s_waitcnt lgkmcnt(7)
	v_lshlrev_b32_e32 v113, 16, v113
	v_fmac_f32_e32 v5, v33, v113
	v_fmac_f32_e32 v6, v32, v113
	v_fmac_f32_e32 v7, v31, v113
	v_fma_f32 v8, v30, v113, v27
	ds_read_u16 v113, v4 offset:5632
	s_waitcnt lgkmcnt(7)
	v_lshlrev_b32_e32 v114, 16, v114
	v_fmac_f32_e32 v5, v34, v114
	v_fmac_f32_e32 v6, v33, v114
	v_fmac_f32_e32 v7, v32, v114
	v_fmac_f32_e32 v8, v31, v114
	v_fma_f32 v9, v30, v114, v27
	ds_read_u16 v114, v4 offset:6144
	s_waitcnt lgkmcnt(7)
	v_lshlrev_b32_e32 v115, 16, v115
	v_fmac_f32_e32 v5, v35, v115
	v_fmac_f32_e32 v6, v34, v115
	v_fmac_f32_e32 v7, v33, v115
	v_fmac_f32_e32 v8, v32, v115
	v_fmac_f32_e32 v9, v31, v115
	v_fma_f32 v10, v30, v115, v27
	ds_read_u16 v115, v4 offset:6656
	s_waitcnt lgkmcnt(7)
	v_lshlrev_b32_e32 v116, 16, v116
	v_fmac_f32_e32 v5, v36, v116
	v_fmac_f32_e32 v6, v35, v116
	v_fmac_f32_e32 v7, v34, v116
	v_fmac_f32_e32 v8, v33, v116
	v_fmac_f32_e32 v9, v32, v116
	v_fmac_f32_e32 v10, v31, v116
	v_fma_f32 v11, v30, v116, v27
	ds_read_u16 v116, v4 offset:7168
	s_waitcnt lgkmcnt(7)
	v_lshlrev_b32_e32 v117, 16, v117
	v_fmac_f32_e32 v5, v37, v117
	v_fmac_f32_e32 v6, v36, v117
	v_fmac_f32_e32 v7, v35, v117
	v_fmac_f32_e32 v8, v34, v117
	v_fmac_f32_e32 v9, v33, v117
	v_fmac_f32_e32 v10, v32, v117
	v_fmac_f32_e32 v11, v31, v117
	v_fma_f32 v12, v30, v117, v27
	ds_read_u16 v117, v4 offset:7680
	s_waitcnt lgkmcnt(7)
	v_lshlrev_b32_e32 v110, 16, v110
	v_fmac_f32_e32 v5, v38, v110
	v_fmac_f32_e32 v6, v37, v110
	v_fmac_f32_e32 v7, v36, v110
	v_fmac_f32_e32 v8, v35, v110
	v_fmac_f32_e32 v9, v34, v110
	v_fmac_f32_e32 v10, v33, v110
	v_fmac_f32_e32 v11, v32, v110
	v_fmac_f32_e32 v12, v31, v110
	ds_read_u16 v110, v4 offset:8192
	s_waitcnt lgkmcnt(7)
	v_lshlrev_b32_e32 v111, 16, v111
	v_fmac_f32_e32 v5, v39, v111
	v_fmac_f32_e32 v6, v38, v111
	v_fmac_f32_e32 v7, v37, v111
	v_fmac_f32_e32 v8, v36, v111
	v_fmac_f32_e32 v9, v35, v111
	v_fmac_f32_e32 v10, v34, v111
	v_fmac_f32_e32 v11, v33, v111
	v_fmac_f32_e32 v12, v32, v111
	ds_read_u16 v111, v4 offset:8704
	s_waitcnt lgkmcnt(7)
	v_lshlrev_b32_e32 v112, 16, v112
	v_fmac_f32_e32 v5, v40, v112
	v_fmac_f32_e32 v6, v39, v112
	v_fmac_f32_e32 v7, v38, v112
	v_fmac_f32_e32 v8, v37, v112
	v_fmac_f32_e32 v9, v36, v112
	v_fmac_f32_e32 v10, v35, v112
	v_fmac_f32_e32 v11, v34, v112
	v_fmac_f32_e32 v12, v33, v112
	ds_read_u16 v112, v4 offset:9216
	s_waitcnt lgkmcnt(7)
	v_lshlrev_b32_e32 v113, 16, v113
	v_fmac_f32_e32 v5, v41, v113
	v_fmac_f32_e32 v6, v40, v113
	v_fmac_f32_e32 v7, v39, v113
	v_fmac_f32_e32 v8, v38, v113
	v_fmac_f32_e32 v9, v37, v113
	v_fmac_f32_e32 v10, v36, v113
	v_fmac_f32_e32 v11, v35, v113
	v_fmac_f32_e32 v12, v34, v113
	ds_read_u16 v113, v4 offset:9728
	s_waitcnt lgkmcnt(7)
	v_lshlrev_b32_e32 v114, 16, v114
	v_fmac_f32_e32 v5, v42, v114
	v_fmac_f32_e32 v6, v41, v114
	v_fmac_f32_e32 v7, v40, v114
	v_fmac_f32_e32 v8, v39, v114
	v_fmac_f32_e32 v9, v38, v114
	v_fmac_f32_e32 v10, v37, v114
	v_fmac_f32_e32 v11, v36, v114
	v_fmac_f32_e32 v12, v35, v114
	ds_read_u16 v114, v4 offset:10240
	s_waitcnt lgkmcnt(7)
	v_lshlrev_b32_e32 v115, 16, v115
	v_fmac_f32_e32 v5, v43, v115
	v_fmac_f32_e32 v6, v42, v115
	v_fmac_f32_e32 v7, v41, v115
	v_fmac_f32_e32 v8, v40, v115
	v_fmac_f32_e32 v9, v39, v115
	v_fmac_f32_e32 v10, v38, v115
	v_fmac_f32_e32 v11, v37, v115
	v_fmac_f32_e32 v12, v36, v115
	ds_read_u16 v115, v4 offset:10752
	s_waitcnt lgkmcnt(7)
	v_lshlrev_b32_e32 v116, 16, v116
	v_fmac_f32_e32 v5, v44, v116
	v_fmac_f32_e32 v6, v43, v116
	v_fmac_f32_e32 v7, v42, v116
	v_fmac_f32_e32 v8, v41, v116
	v_fmac_f32_e32 v9, v40, v116
	v_fmac_f32_e32 v10, v39, v116
	v_fmac_f32_e32 v11, v38, v116
	v_fmac_f32_e32 v12, v37, v116
	ds_read_u16 v116, v4 offset:11264
	s_waitcnt lgkmcnt(7)
	v_lshlrev_b32_e32 v117, 16, v117
	v_fmac_f32_e32 v5, v45, v117
	v_fmac_f32_e32 v6, v44, v117
	v_fmac_f32_e32 v7, v43, v117
	v_fmac_f32_e32 v8, v42, v117
	v_fmac_f32_e32 v9, v41, v117
	v_fmac_f32_e32 v10, v40, v117
	v_fmac_f32_e32 v11, v39, v117
	v_fmac_f32_e32 v12, v38, v117
	ds_read_u16 v117, v4 offset:11776
	s_waitcnt lgkmcnt(7)
	v_lshlrev_b32_e32 v110, 16, v110
	v_fmac_f32_e32 v5, v46, v110
	v_fmac_f32_e32 v6, v45, v110
	v_fmac_f32_e32 v7, v44, v110
	v_fmac_f32_e32 v8, v43, v110
	v_fmac_f32_e32 v9, v42, v110
	v_fmac_f32_e32 v10, v41, v110
	v_fmac_f32_e32 v11, v40, v110
	v_fmac_f32_e32 v12, v39, v110
	ds_read_u16 v110, v4 offset:12288
	s_waitcnt lgkmcnt(7)
	v_lshlrev_b32_e32 v111, 16, v111
	v_fmac_f32_e32 v5, v47, v111
	v_fmac_f32_e32 v6, v46, v111
	v_fmac_f32_e32 v7, v45, v111
	v_fmac_f32_e32 v8, v44, v111
	v_fmac_f32_e32 v9, v43, v111
	v_fmac_f32_e32 v10, v42, v111
	v_fmac_f32_e32 v11, v41, v111
	v_fmac_f32_e32 v12, v40, v111
	ds_read_u16 v111, v4 offset:12800
	s_waitcnt lgkmcnt(7)
	v_lshlrev_b32_e32 v112, 16, v112
	v_fmac_f32_e32 v5, v48, v112
	v_fmac_f32_e32 v6, v47, v112
	v_fmac_f32_e32 v7, v46, v112
	v_fmac_f32_e32 v8, v45, v112
	v_fmac_f32_e32 v9, v44, v112
	v_fmac_f32_e32 v10, v43, v112
	v_fmac_f32_e32 v11, v42, v112
	v_fmac_f32_e32 v12, v41, v112
	ds_read_u16 v112, v4 offset:13312
	s_waitcnt lgkmcnt(7)
	v_lshlrev_b32_e32 v113, 16, v113
	v_fmac_f32_e32 v5, v49, v113
	v_fmac_f32_e32 v6, v48, v113
	v_fmac_f32_e32 v7, v47, v113
	v_fmac_f32_e32 v8, v46, v113
	v_fmac_f32_e32 v9, v45, v113
	v_fmac_f32_e32 v10, v44, v113
	v_fmac_f32_e32 v11, v43, v113
	v_fmac_f32_e32 v12, v42, v113
	ds_read_u16 v113, v4 offset:13824
	s_waitcnt lgkmcnt(7)
	v_lshlrev_b32_e32 v114, 16, v114
	v_fmac_f32_e32 v5, v50, v114
	v_fmac_f32_e32 v6, v49, v114
	v_fmac_f32_e32 v7, v48, v114
	v_fmac_f32_e32 v8, v47, v114
	v_fmac_f32_e32 v9, v46, v114
	v_fmac_f32_e32 v10, v45, v114
	v_fmac_f32_e32 v11, v44, v114
	v_fmac_f32_e32 v12, v43, v114
	ds_read_u16 v114, v4 offset:14336
	s_waitcnt lgkmcnt(7)
	v_lshlrev_b32_e32 v115, 16, v115
	v_fmac_f32_e32 v5, v51, v115
	v_fmac_f32_e32 v6, v50, v115
	v_fmac_f32_e32 v7, v49, v115
	v_fmac_f32_e32 v8, v48, v115
	v_fmac_f32_e32 v9, v47, v115
	v_fmac_f32_e32 v10, v46, v115
	v_fmac_f32_e32 v11, v45, v115
	v_fmac_f32_e32 v12, v44, v115
	ds_read_u16 v115, v4 offset:14848
	s_waitcnt lgkmcnt(7)
	v_lshlrev_b32_e32 v116, 16, v116
	v_fmac_f32_e32 v5, v52, v116
	v_fmac_f32_e32 v6, v51, v116
	v_fmac_f32_e32 v7, v50, v116
	v_fmac_f32_e32 v8, v49, v116
	v_fmac_f32_e32 v9, v48, v116
	v_fmac_f32_e32 v10, v47, v116
	v_fmac_f32_e32 v11, v46, v116
	v_fmac_f32_e32 v12, v45, v116
	ds_read_u16 v116, v4 offset:15360
	s_waitcnt lgkmcnt(7)
	v_lshlrev_b32_e32 v117, 16, v117
	v_fmac_f32_e32 v5, v53, v117
	v_fmac_f32_e32 v6, v52, v117
	v_fmac_f32_e32 v7, v51, v117
	v_fmac_f32_e32 v8, v50, v117
	v_fmac_f32_e32 v9, v49, v117
	v_fmac_f32_e32 v10, v48, v117
	v_fmac_f32_e32 v11, v47, v117
	v_fmac_f32_e32 v12, v46, v117
	ds_read_u16 v117, v4 offset:15872
	s_waitcnt lgkmcnt(7)
	v_lshlrev_b32_e32 v110, 16, v110
	v_fmac_f32_e32 v5, v54, v110
	v_fmac_f32_e32 v6, v53, v110
	v_fmac_f32_e32 v7, v52, v110
	v_fmac_f32_e32 v8, v51, v110
	v_fmac_f32_e32 v9, v50, v110
	v_fmac_f32_e32 v10, v49, v110
	v_fmac_f32_e32 v11, v48, v110
	v_fmac_f32_e32 v12, v47, v110
	ds_read_u16 v110, v4 offset:16384
	s_waitcnt lgkmcnt(7)
	v_lshlrev_b32_e32 v111, 16, v111
	v_fmac_f32_e32 v5, v55, v111
	v_fmac_f32_e32 v6, v54, v111
	v_fmac_f32_e32 v7, v53, v111
	v_fmac_f32_e32 v8, v52, v111
	v_fmac_f32_e32 v9, v51, v111
	v_fmac_f32_e32 v10, v50, v111
	v_fmac_f32_e32 v11, v49, v111
	v_fmac_f32_e32 v12, v48, v111
	ds_read_u16 v111, v4 offset:16896
	s_waitcnt lgkmcnt(7)
	v_lshlrev_b32_e32 v112, 16, v112
	v_fmac_f32_e32 v5, v56, v112
	v_fmac_f32_e32 v6, v55, v112
	v_fmac_f32_e32 v7, v54, v112
	v_fmac_f32_e32 v8, v53, v112
	v_fmac_f32_e32 v9, v52, v112
	v_fmac_f32_e32 v10, v51, v112
	v_fmac_f32_e32 v11, v50, v112
	v_fmac_f32_e32 v12, v49, v112
	ds_read_u16 v112, v4 offset:17408
	s_waitcnt lgkmcnt(7)
	v_lshlrev_b32_e32 v113, 16, v113
	v_fmac_f32_e32 v5, v57, v113
	v_fmac_f32_e32 v6, v56, v113
	v_fmac_f32_e32 v7, v55, v113
	v_fmac_f32_e32 v8, v54, v113
	v_fmac_f32_e32 v9, v53, v113
	v_fmac_f32_e32 v10, v52, v113
	v_fmac_f32_e32 v11, v51, v113
	v_fmac_f32_e32 v12, v50, v113
	ds_read_u16 v113, v4 offset:17920
	s_waitcnt lgkmcnt(7)
	v_lshlrev_b32_e32 v114, 16, v114
	v_fmac_f32_e32 v5, v58, v114
	v_fmac_f32_e32 v6, v57, v114
	v_fmac_f32_e32 v7, v56, v114
	v_fmac_f32_e32 v8, v55, v114
	v_fmac_f32_e32 v9, v54, v114
	v_fmac_f32_e32 v10, v53, v114
	v_fmac_f32_e32 v11, v52, v114
	v_fmac_f32_e32 v12, v51, v114
	ds_read_u16 v114, v4 offset:18432
	s_waitcnt lgkmcnt(7)
	v_lshlrev_b32_e32 v115, 16, v115
	v_fmac_f32_e32 v5, v59, v115
	v_fmac_f32_e32 v6, v58, v115
	v_fmac_f32_e32 v7, v57, v115
	v_fmac_f32_e32 v8, v56, v115
	v_fmac_f32_e32 v9, v55, v115
	v_fmac_f32_e32 v10, v54, v115
	v_fmac_f32_e32 v11, v53, v115
	v_fmac_f32_e32 v12, v52, v115
	ds_read_u16 v115, v4 offset:18944
	s_waitcnt lgkmcnt(7)
	v_lshlrev_b32_e32 v116, 16, v116
	v_fmac_f32_e32 v5, v60, v116
	v_fmac_f32_e32 v6, v59, v116
	v_fmac_f32_e32 v7, v58, v116
	v_fmac_f32_e32 v8, v57, v116
	v_fmac_f32_e32 v9, v56, v116
	v_fmac_f32_e32 v10, v55, v116
	v_fmac_f32_e32 v11, v54, v116
	v_fmac_f32_e32 v12, v53, v116
	s_waitcnt lgkmcnt(6)
	v_lshlrev_b32_e32 v117, 16, v117
	v_fmac_f32_e32 v6, v60, v117
	v_fmac_f32_e32 v7, v59, v117
	v_fmac_f32_e32 v8, v58, v117
	v_fmac_f32_e32 v9, v57, v117
	v_fmac_f32_e32 v10, v56, v117
	v_fmac_f32_e32 v11, v55, v117
	v_fmac_f32_e32 v12, v54, v117
	s_waitcnt lgkmcnt(5)
	v_lshlrev_b32_e32 v110, 16, v110
	v_fmac_f32_e32 v7, v60, v110
	v_fmac_f32_e32 v8, v59, v110
	v_fmac_f32_e32 v9, v58, v110
	v_fmac_f32_e32 v10, v57, v110
	v_fmac_f32_e32 v11, v56, v110
	v_fmac_f32_e32 v12, v55, v110
	s_waitcnt lgkmcnt(4)
	v_lshlrev_b32_e32 v111, 16, v111
	v_fmac_f32_e32 v8, v60, v111
	v_fmac_f32_e32 v9, v59, v111
	v_fmac_f32_e32 v10, v58, v111
	v_fmac_f32_e32 v11, v57, v111
	v_fmac_f32_e32 v12, v56, v111
	s_waitcnt lgkmcnt(3)
	v_lshlrev_b32_e32 v112, 16, v112
	v_fmac_f32_e32 v9, v60, v112
	v_fmac_f32_e32 v10, v59, v112
	v_fmac_f32_e32 v11, v58, v112
	v_fmac_f32_e32 v12, v57, v112
	s_waitcnt lgkmcnt(2)
	v_lshlrev_b32_e32 v113, 16, v113
	v_fmac_f32_e32 v10, v60, v113
	v_fmac_f32_e32 v11, v59, v113
	v_fmac_f32_e32 v12, v58, v113
	s_waitcnt lgkmcnt(1)
	v_lshlrev_b32_e32 v114, 16, v114
	v_fmac_f32_e32 v12, v59, v114
	v_fmac_f32_e32 v11, v60, v114
	s_waitcnt lgkmcnt(0)
	v_lshlrev_b32_e32 v115, 16, v115
	v_fmac_f32_e32 v12, v60, v115
	s_addk_i32 s0, 0x1000
	s_cmpk_eq_i32 s0, 0x4000
	ds_write_b32 v2, v5
	ds_write_b32 v2, v6 offset:1040
	ds_write_b32 v2, v7 offset:2080
	ds_write_b32 v2, v8 offset:3120
	ds_write_b32 v2, v9 offset:4160
	ds_write_b32 v2, v10 offset:5200
	ds_write_b32 v2, v11 offset:6240
	ds_write_b32 v2, v12 offset:7280
	v_add_u32_e32 v2, 0x2080, v2
	s_cbranch_scc0 .LBB0_538
	v_ashrrev_i32_e32 v91, 6, v1
	v_and_b32_e32 v83, 15, v1
	v_lshl_or_b32 v2, v91, 5, v83
	v_ashrrev_i32_e32 v3, 31, v2
	v_lshrrev_b32_e32 v4, 1, v1
	v_lshlrev_b64 v[2:3], 9, v[2:3]
	v_and_b32_e32 v75, 24, v4
	v_lshl_add_u64 v[2:3], s[18:19], 0, v[2:3]
	v_lshlrev_b32_e32 v4, 1, v75
	v_mov_b32_e32 v5, v0
	v_lshl_add_u64 v[2:3], v[2:3], 0, v[4:5]
	s_movk_i32 s0, 0x2000
	v_add_co_u32_e32 v6, vcc, s0, v2
	s_waitcnt lgkmcnt(0)
	s_nop 0
	v_addc_co_u32_e32 v7, vcc, 0, v3, vcc
	s_barrier
	global_load_dwordx4 v[58:61], v[2:3], off
	global_load_dwordx4 v[50:53], v[2:3], off offset:64
	global_load_dwordx4 v[62:65], v[6:7], off
	global_load_dwordx4 v[54:57], v[6:7], off offset:64
	global_load_dwordx4 v[42:45], v[2:3], off offset:128
	global_load_dwordx4 v[34:37], v[2:3], off offset:192
	global_load_dwordx4 v[46:49], v[6:7], off offset:128
	global_load_dwordx4 v[38:41], v[6:7], off offset:192
	global_load_dwordx4 v[26:29], v[2:3], off offset:256
	global_load_dwordx4 v[18:21], v[2:3], off offset:320
	global_load_dwordx4 v[30:33], v[6:7], off offset:256
	global_load_dwordx4 v[22:25], v[6:7], off offset:320
	global_load_dwordx4 v[10:13], v[2:3], off offset:384
	s_nop 0
	global_load_dwordx4 v[2:5], v[2:3], off offset:448
	s_nop 0
	global_load_dwordx4 v[14:17], v[6:7], off offset:384
	s_nop 0
	global_load_dwordx4 v[6:9], v[6:7], off offset:448
	v_and_b32_e32 v84, 63, v1
	v_lshlrev_b32_e32 v78, 4, v84
	v_mov_b32_e32 v79, v0
	v_lshl_add_u64 v[66:67], s[26:27], 0, v[78:79]
	v_lshl_add_u64 v[70:71], s[28:29], 0, v[78:79]
	global_load_dwordx4 v[66:69], v[66:67], off
	v_lshlrev_b32_e32 v79, 2, v84
	global_load_dwordx4 v[70:73], v[70:71], off
	s_movk_i32 s1, 0x1080
	v_lshlrev_b32_e32 v90, 3, v84
	v_xor_b32_e32 v84, 4, v79
	v_xor_b32_e32 v85, 8, v79
	v_xor_b32_e32 v86, 16, v79
	v_xor_b32_e32 v87, 32, v79
	v_xor_b32_e32 v88, 64, v79
	v_xor_b32_e32 v89, 0x80, v79
	v_mul_lo_u32 v79, v91, s1
	s_movk_i32 s1, 0x2080
	v_add3_u32 v90, v79, v90, 0
	v_mul_lo_u32 v79, v91, s1
	v_readlane_b32 s1, v254, 45
	s_mov_b32 s0, 0
	s_nop 0
	v_add3_u32 v91, v79, v78, s1
